# v1 + QKPREP raw-v copy loads hoisted to row top + NORM_MLP row loads batched (12 in flight, counted vmcnt)
# baseline (speedup 1.0000x reference)
.LBB0_74:
	global_load_dwordx4 v[12:15], v[4:5], off offset:-2048
	global_load_dwordx4 v[16:19], v[4:5], off offset:-1024
	global_load_dwordx4 v[20:23], v[4:5], off
	global_load_dwordx4 v[24:27], v[4:5], off offset:1024
	s_cmpk_lt_u32 s6, 0x2800
	s_cselect_b32 s0, s76, 0x3000
	s_cmpk_gt_i32 s6, 0x1fff
	s_cselect_b32 s0, s0, 0
	s_lshl_b32 s0, s0, 2
	s_add_u32 s0, s4, s0
	s_addc_u32 s1, s5, 0
	v_lshl_add_u64 v[84:85], s[0:1], 0, v[0:1]
	global_load_dwordx4 v[52:55], v0, s[0:1]
	v_lshl_add_u64 v[84:85], v[84:85], 0, s[12:13]
	s_add_i32 s6, s6, s70
	global_load_dwordx4 v[56:59], v[84:85], off
	global_load_dwordx4 v[60:63], v0, s[0:1] offset:1024
	global_load_dwordx4 v[64:67], v[84:85], off offset:1024
	global_load_dwordx4 v[68:71], v0, s[0:1] offset:2048
	global_load_dwordx4 v[72:75], v[84:85], off offset:2048
	global_load_dwordx4 v[76:79], v0, s[0:1] offset:3072
	global_load_dwordx4 v[80:83], v[84:85], off offset:3072
	s_cmpk_gt_i32 s6, 0x2fff
	s_waitcnt vmcnt(11)
	v_pk_mul_f32 v[40:41], v[14:15], v[14:15]
	v_pk_mul_f32 v[42:43], v[12:13], v[12:13]
	s_nop 0
	v_pk_mov_b32 v[44:45], v[42:43], v[40:41] op_sel:[1,0]
	v_mov_b32_e32 v43, v41
	v_pk_add_f32 v[28:29], v[44:45], v[42:43]
	s_nop 0
	v_pk_add_f32 v[28:29], v[28:29], v[28:29] op_sel:[0,1] op_sel_hi:[1,0]
	s_waitcnt vmcnt(10)
	v_pk_mul_f32 v[46:47], v[18:19], v[18:19]
	v_pk_mul_f32 v[48:49], v[16:17], v[16:17]
	s_nop 0
	v_pk_mov_b32 v[50:51], v[48:49], v[46:47] op_sel:[1,0]
	v_mov_b32_e32 v49, v47
	v_pk_add_f32 v[30:31], v[50:51], v[48:49]
	s_nop 0
	v_pk_add_f32 v[30:31], v[30:31], v[30:31] op_sel:[0,1] op_sel_hi:[1,0]
	v_lshl_add_u64 v[4:5], v[4:5], 0, s[96:97]
	s_waitcnt vmcnt(8)
	v_mul_f32_e32 v32, v24, v24
	v_mul_f32_e32 v33, v25, v25
	v_mov_b32_e32 v29, v32
	v_mov_b32_e32 v31, v33
	v_pk_add_f32 v[28:29], v[28:29], v[30:31]
	v_mul_f32_e32 v30, v21, v21
	v_mul_f32_e32 v32, v23, v23
	v_mul_f32_e32 v34, v26, v26
	v_mul_f32_e32 v35, v27, v27
	v_pk_fma_f32 v[30:31], v[20:21], v[20:21], v[30:31] op_sel_hi:[1,1,0]
	v_pk_fma_f32 v[32:33], v[22:23], v[22:23], v[32:33] op_sel_hi:[1,1,0]
	v_mov_b32_e32 v31, v34
	v_mov_b32_e32 v33, v35
	v_pk_add_f32 v[30:31], v[30:31], v[32:33]
	s_nop 0
	v_pk_add_f32 v[28:29], v[28:29], v[30:31]
	s_nop 0
	v_add_f32_e32 v28, v28, v29
	ds_bpermute_b32 v29, v6, v28
	s_waitcnt lgkmcnt(0)
	v_add_f32_e32 v28, v28, v29
	ds_bpermute_b32 v29, v7, v28
	s_waitcnt lgkmcnt(0)
	v_add_f32_e32 v28, v28, v29
	ds_bpermute_b32 v29, v8, v28
	s_waitcnt lgkmcnt(0)
	v_add_f32_e32 v28, v28, v29
	ds_bpermute_b32 v29, v9, v28
	s_waitcnt lgkmcnt(0)
	v_add_f32_e32 v28, v28, v29
	ds_bpermute_b32 v29, v10, v28
	s_waitcnt lgkmcnt(0)
	v_add_f32_e32 v28, v28, v29
	ds_bpermute_b32 v29, v11, v28
	s_waitcnt lgkmcnt(0)
	v_add_f32_e32 v28, v28, v29
	v_fmamk_f32 v28, v28, 0x3a800000, v213
	v_cmp_gt_f32_e32 vcc, s7, v28
	v_mul_f32_e32 v29, 0x4b800000, v28
	s_nop 0
	v_cndmask_b32_e32 v28, v28, v29, vcc
	v_rsq_f32_e32 v28, v28
	s_nop 0
	v_mul_f32_e32 v29, 0x45800000, v28
	v_cndmask_b32_e32 v36, v28, v29, vcc
	v_pk_mul_f32 v[12:13], v[12:13], v[36:37] op_sel_hi:[1,0]
	v_pk_mul_f32 v[14:15], v[14:15], v[36:37] op_sel_hi:[1,0]
	v_pk_mul_f32 v[16:17], v[16:17], v[36:37] op_sel_hi:[1,0]
	v_pk_mul_f32 v[18:19], v[18:19], v[36:37] op_sel_hi:[1,0]
	v_pk_mul_f32 v[20:21], v[20:21], v[36:37] op_sel_hi:[1,0]
	v_pk_mul_f32 v[22:23], v[22:23], v[36:37] op_sel_hi:[1,0]
	v_pk_mul_f32 v[24:25], v[24:25], v[36:37] op_sel_hi:[1,0]
	v_pk_mul_f32 v[26:27], v[26:27], v[36:37] op_sel_hi:[1,0]
	s_waitcnt vmcnt(6)
	v_pk_add_f32 v[58:59], v[58:59], 1.0 op_sel_hi:[1,0]
	v_pk_add_f32 v[56:57], v[56:57], 1.0 op_sel_hi:[1,0]
	v_pk_fma_f32 v[34:35], v[58:59], v[14:15], v[54:55]
	v_pk_fma_f32 v[32:33], v[56:57], v[12:13], v[52:53]
	s_waitcnt vmcnt(4)
	v_pk_add_f32 v[66:67], v[66:67], 1.0 op_sel_hi:[1,0]
	v_pk_add_f32 v[64:65], v[64:65], 1.0 op_sel_hi:[1,0]
	v_pk_fma_f32 v[30:31], v[66:67], v[18:19], v[62:63]
	v_pk_fma_f32 v[28:29], v[64:65], v[16:17], v[60:61]
	s_waitcnt vmcnt(2)
	v_pk_add_f32 v[74:75], v[74:75], 1.0 op_sel_hi:[1,0]
	v_pk_add_f32 v[72:73], v[72:73], 1.0 op_sel_hi:[1,0]
	v_pk_fma_f32 v[22:23], v[74:75], v[22:23], v[70:71]
	v_pk_fma_f32 v[20:21], v[72:73], v[20:21], v[68:69]
	s_waitcnt vmcnt(0)
	v_pk_add_f32 v[80:81], v[80:81], 1.0 op_sel_hi:[1,0]
	v_pk_add_f32 v[82:83], v[82:83], 1.0 op_sel_hi:[1,0]
	v_pk_fma_f32 v[12:13], v[80:81], v[24:25], v[76:77]
	v_cvt_pk_bf16_f32 v16, v32, v33
	v_cvt_pk_bf16_f32 v17, v34, v35
	v_pk_fma_f32 v[14:15], v[82:83], v[26:27], v[78:79]
	global_store_dwordx2 v[2:3], v[16:17], off offset:-1536
	v_cvt_pk_bf16_f32 v18, v28, v29
	v_cvt_pk_bf16_f32 v19, v30, v31
	global_store_dwordx2 v[2:3], v[18:19], off offset:-1024
	v_cvt_pk_bf16_f32 v40, v20, v21
	v_cvt_pk_bf16_f32 v41, v22, v23
	v_cvt_pk_bf16_f32 v12, v12, v13
	v_cvt_pk_bf16_f32 v13, v14, v15
	global_store_dwordx2 v[2:3], v[40:41], off offset:-512
	global_store_dwordx2 v[2:3], v[12:13], off
	v_lshl_add_u64 v[2:3], v[2:3], 0, s[8:9]
	s_cbranch_scc0 .LBB0_74

.LBB0_757:
	s_cmpk_gt_i32 s13, 0x1fff
	s_cselect_b64 s[52:53], -1, 0
	s_cmpk_lt_i32 s13, 0x2000
	s_cselect_b64 s[36:37], -1, 0
	s_cbranch_scc0 .Lmy_vc_ld_end
	global_load_dwordx2 v[142:143], v[42:43], off
	s_cmpk_lt_u32 s1, 0x400
	s_cbranch_scc1 .Lmy_vc_ld_end
	global_load_dwordx2 v[144:145], v[42:43], off offset:512
	global_load_dwordx2 v[146:147], v[42:43], off offset:1024
	global_load_dwordx2 v[148:149], v[42:43], off offset:1536
.Lmy_vc_ld_end:
	s_ashr_i32 s19, s13, 8
	s_and_saveexec_b64 s[38:39], s[40:41]
	s_cbranch_execz .Lmy_vc_wait0
	s_mul_hi_i32 s17, s0, s13
	s_mul_i32 s16, s0, s13
	v_lshl_add_u64 v[46:47], s[16:17], 1, v[36:37]
	global_load_dwordx4 v[18:21], v[46:47], off offset:48
	global_load_dwordx4 v[22:25], v[46:47], off
	global_load_dwordx4 v[26:29], v[46:47], off offset:16
	global_load_dwordx4 v[30:33], v[46:47], off offset:32
	global_load_dwordx4 v[2:5], v[38:39], off offset:48
	global_load_dwordx4 v[6:9], v[38:39], off offset:32
	global_load_dwordx4 v[10:13], v[38:39], off offset:16
	global_load_dwordx4 v[14:17], v[38:39], off
	global_load_dwordx4 v[50:53], v[38:39], off offset:112
	global_load_dwordx4 v[54:57], v[38:39], off offset:96
	global_load_dwordx4 v[58:61], v[38:39], off offset:80
	global_load_dwordx4 v[62:65], v[38:39], off offset:64
	s_waitcnt vmcnt(11)
	v_and_b32_e32 v66, 0xffff0000, v20
	v_lshlrev_b32_e32 v67, 16, v20
	v_and_b32_e32 v68, 0xffff0000, v21
	v_lshlrev_b32_e32 v69, 16, v21
	s_waitcnt vmcnt(10)
	v_lshlrev_b32_e32 v20, 16, v22
	v_and_b32_e32 v21, 0xffff0000, v22
	v_lshlrev_b32_e32 v22, 16, v23
	v_and_b32_e32 v23, 0xffff0000, v23
	v_pk_mul_f32 v[86:87], v[20:21], v[20:21]
	v_pk_mul_f32 v[88:89], v[22:23], v[22:23]
	v_add_f32_e32 v49, v86, v87
	v_lshlrev_b32_e32 v70, 16, v24
	v_and_b32_e32 v71, 0xffff0000, v24
	v_add_f32_e32 v49, v88, v49
	v_pk_mul_f32 v[90:91], v[70:71], v[70:71]
	v_add_f32_e32 v49, v89, v49
	v_lshlrev_b32_e32 v24, 16, v25
	v_and_b32_e32 v25, 0xffff0000, v25
	v_add_f32_e32 v49, v90, v49
	v_pk_mul_f32 v[92:93], v[24:25], v[24:25]
	v_add_f32_e32 v49, v91, v49
	s_waitcnt vmcnt(9)
	v_lshlrev_b32_e32 v72, 16, v26
	v_and_b32_e32 v73, 0xffff0000, v26
	v_add_f32_e32 v49, v92, v49
	v_pk_mul_f32 v[94:95], v[72:73], v[72:73]
	v_add_f32_e32 v49, v93, v49
	v_lshlrev_b32_e32 v26, 16, v27
	v_and_b32_e32 v27, 0xffff0000, v27
	v_add_f32_e32 v49, v94, v49
	v_pk_mul_f32 v[96:97], v[26:27], v[26:27]
	v_add_f32_e32 v49, v95, v49
	v_lshlrev_b32_e32 v74, 16, v28
	v_and_b32_e32 v75, 0xffff0000, v28
	v_add_f32_e32 v49, v96, v49
	v_pk_mul_f32 v[98:99], v[74:75], v[74:75]
	v_add_f32_e32 v49, v97, v49
	v_lshlrev_b32_e32 v28, 16, v29
	v_and_b32_e32 v29, 0xffff0000, v29
	v_add_f32_e32 v49, v98, v49
	v_pk_mul_f32 v[100:101], v[28:29], v[28:29]
	v_add_f32_e32 v49, v99, v49
	s_waitcnt vmcnt(8)
	v_lshlrev_b32_e32 v76, 16, v30
	v_and_b32_e32 v77, 0xffff0000, v30
	v_add_f32_e32 v49, v100, v49
	v_pk_mul_f32 v[86:87], v[76:77], v[76:77]
	v_add_f32_e32 v49, v101, v49
	v_lshlrev_b32_e32 v30, 16, v31
	v_and_b32_e32 v31, 0xffff0000, v31
	v_add_f32_e32 v49, v86, v49
	v_pk_mul_f32 v[88:89], v[30:31], v[30:31]
	v_add_f32_e32 v49, v87, v49
	v_lshlrev_b32_e32 v78, 16, v32
	v_and_b32_e32 v79, 0xffff0000, v32
	v_add_f32_e32 v49, v88, v49
	v_pk_mul_f32 v[90:91], v[78:79], v[78:79]
	v_add_f32_e32 v49, v89, v49
	v_lshlrev_b32_e32 v32, 16, v33
	v_and_b32_e32 v33, 0xffff0000, v33
	v_add_f32_e32 v49, v90, v49
	v_pk_mul_f32 v[92:93], v[32:33], v[32:33]
	v_add_f32_e32 v49, v91, v49
	v_lshlrev_b32_e32 v80, 16, v18
	v_and_b32_e32 v81, 0xffff0000, v18
	v_add_f32_e32 v49, v92, v49
	v_pk_mul_f32 v[94:95], v[80:81], v[80:81]
	v_add_f32_e32 v49, v93, v49
	v_lshlrev_b32_e32 v82, 16, v19
	v_and_b32_e32 v83, 0xffff0000, v19
	v_add_f32_e32 v49, v94, v49
	v_pk_mul_f32 v[96:97], v[82:83], v[82:83]
	v_add_f32_e32 v49, v95, v49
	v_add_f32_e32 v49, v96, v49
	v_pk_mul_f32 v[18:19], v[66:67], v[66:67]
	v_add_f32_e32 v49, v97, v49
	v_add_f32_e32 v19, v19, v49
	v_pk_mul_f32 v[84:85], v[68:69], v[68:69]
	v_add_f32_e32 v18, v18, v19
	v_add_f32_e32 v18, v85, v18
	v_add_f32_e32 v18, v84, v18
	s_nop 1
	v_add_f32_dpp v18, v18, v18 quad_perm:[1,0,3,2] row_mask:0xf bank_mask:0xf bound_ctrl:1
	v_fmamk_f32 v18, v18, 0x3c800000, v213
	v_mul_f32_e32 v19, 0x4b800000, v18
	v_cmp_gt_f32_e32 vcc, s79, v18
	s_nop 1
	v_cndmask_b32_e32 v18, v18, v19, vcc
	v_rsq_f32_e32 v18, v18
	s_nop 0
	v_mul_f32_e32 v19, 0x45800000, v18
	v_cndmask_b32_e32 v84, v18, v19, vcc
	v_pk_mul_f32 v[18:19], v[84:85], v[20:21] op_sel_hi:[0,1]
	v_pk_mul_f32 v[74:75], v[84:85], v[74:75] op_sel_hi:[0,1]
	v_pk_mul_f32 v[20:21], v[84:85], v[22:23] op_sel_hi:[0,1]
	v_pk_mul_f32 v[22:23], v[84:85], v[70:71] op_sel_hi:[0,1]
	v_pk_mul_f32 v[24:25], v[84:85], v[24:25] op_sel_hi:[0,1]
	v_pk_mul_f32 v[70:71], v[84:85], v[72:73] op_sel_hi:[0,1]
	v_pk_mul_f32 v[72:73], v[84:85], v[26:27] op_sel_hi:[0,1]
	v_pk_mul_f32 v[86:87], v[84:85], v[28:29] op_sel_hi:[0,1]
	v_pk_mul_f32 v[88:89], v[84:85], v[30:31] op_sel_hi:[0,1]
	s_waitcnt vmcnt(4)
	v_pk_mul_f32 v[30:31], v[14:15], v[18:19]
	v_pk_mul_f32 v[18:19], v[2:3], v[74:75]
	v_pk_mul_f32 v[2:3], v[84:85], v[82:83] op_sel_hi:[0,1]
	v_pk_mul_f32 v[76:77], v[84:85], v[76:77] op_sel_hi:[0,1]
	v_pk_mul_f32 v[78:79], v[84:85], v[78:79] op_sel_hi:[0,1]
	v_pk_mul_f32 v[90:91], v[84:85], v[32:33] op_sel_hi:[0,1]
	v_pk_mul_f32 v[80:81], v[84:85], v[80:81] op_sel_hi:[0,1]
	v_pk_mul_f32 v[32:33], v[16:17], v[20:21]
	v_pk_mul_f32 v[28:29], v[12:13], v[24:25]
	v_pk_mul_f32 v[24:25], v[8:9], v[72:73]
	v_pk_mul_f32 v[20:21], v[4:5], v[86:87]
	s_waitcnt vmcnt(2)
	v_pk_mul_f32 v[8:9], v[56:57], v[2:3]
	v_pk_mul_f32 v[2:3], v[84:85], v[66:67] op_sel_hi:[0,1]
	v_pk_mul_f32 v[4:5], v[84:85], v[68:69] op_sel_hi:[0,1]
	v_pk_mul_f32 v[26:27], v[10:11], v[22:23]
	v_pk_mul_f32 v[22:23], v[6:7], v[70:71]
	s_waitcnt vmcnt(0)
	v_pk_mul_f32 v[14:15], v[62:63], v[76:77]
	v_pk_mul_f32 v[16:17], v[64:65], v[88:89]
	v_pk_mul_f32 v[10:11], v[58:59], v[78:79]
	v_pk_mul_f32 v[12:13], v[60:61], v[90:91]
	v_pk_mul_f32 v[6:7], v[54:55], v[80:81]
	v_pk_mul_f32 v[2:3], v[50:51], v[2:3] op_sel:[0,1] op_sel_hi:[1,0]
	s_andn2_b64 vcc, exec, s[52:53]
	v_pk_mul_f32 v[4:5], v[52:53], v[4:5] op_sel:[0,1] op_sel_hi:[1,0]
	s_cbranch_vccnz .LBB0_762
	s_max_i32 s16, s13, 0x2000
	s_lshl_b32 s16, s16, 7
	s_and_b32 s16, s16, 0x3ff80
	v_mov_b32_e32 v49, s16
	global_load_dwordx4 v[50:53], v49, s[30:31]
	global_load_dwordx4 v[54:57], v49, s[30:31] offset:16
	global_load_dwordx4 v[58:61], v49, s[30:31] offset:32
	global_load_dwordx4 v[62:65], v49, s[30:31] offset:48
	global_load_dwordx4 v[66:69], v49, s[30:31] offset:64
	global_load_dwordx4 v[70:73], v49, s[30:31] offset:80
	global_load_dwordx4 v[74:77], v49, s[30:31] offset:96
	global_load_dwordx4 v[78:81], v49, s[30:31] offset:112
	global_load_dwordx4 v[82:85], v49, s[28:29] offset:112
	global_load_dwordx4 v[86:89], v49, s[28:29] offset:96
	global_load_dwordx4 v[90:93], v49, s[28:29] offset:80
	global_load_dwordx4 v[94:97], v49, s[28:29] offset:64
	global_load_dwordx4 v[98:101], v49, s[28:29] offset:48
	global_load_dwordx4 v[102:105], v49, s[28:29] offset:32
	global_load_dwordx4 v[106:109], v49, s[28:29] offset:16
	global_load_dwordx4 v[110:113], v49, s[28:29]
	v_mov_b32_dpp v114, v30 quad_perm:[1,0,3,2] row_mask:0xf bank_mask:0xf bound_ctrl:1
	v_mov_b32_dpp v115, v31 quad_perm:[1,0,3,2] row_mask:0xf bank_mask:0xf bound_ctrl:1
	v_mov_b32_dpp v116, v32 quad_perm:[1,0,3,2] row_mask:0xf bank_mask:0xf bound_ctrl:1
	v_mov_b32_dpp v117, v33 quad_perm:[1,0,3,2] row_mask:0xf bank_mask:0xf bound_ctrl:1
	v_mov_b32_dpp v118, v26 quad_perm:[1,0,3,2] row_mask:0xf bank_mask:0xf bound_ctrl:1
	v_mov_b32_dpp v119, v27 quad_perm:[1,0,3,2] row_mask:0xf bank_mask:0xf bound_ctrl:1
	v_mov_b32_dpp v120, v28 quad_perm:[1,0,3,2] row_mask:0xf bank_mask:0xf bound_ctrl:1
	v_mov_b32_dpp v121, v29 quad_perm:[1,0,3,2] row_mask:0xf bank_mask:0xf bound_ctrl:1
	v_mov_b32_dpp v122, v22 quad_perm:[1,0,3,2] row_mask:0xf bank_mask:0xf bound_ctrl:1
	v_mov_b32_dpp v123, v23 quad_perm:[1,0,3,2] row_mask:0xf bank_mask:0xf bound_ctrl:1
	v_mov_b32_dpp v124, v24 quad_perm:[1,0,3,2] row_mask:0xf bank_mask:0xf bound_ctrl:1
	v_mov_b32_dpp v125, v25 quad_perm:[1,0,3,2] row_mask:0xf bank_mask:0xf bound_ctrl:1
	v_mov_b32_dpp v126, v18 quad_perm:[1,0,3,2] row_mask:0xf bank_mask:0xf bound_ctrl:1
	v_mov_b32_dpp v127, v19 quad_perm:[1,0,3,2] row_mask:0xf bank_mask:0xf bound_ctrl:1
	v_mov_b32_dpp v128, v20 quad_perm:[1,0,3,2] row_mask:0xf bank_mask:0xf bound_ctrl:1
	v_mov_b32_dpp v129, v21 quad_perm:[1,0,3,2] row_mask:0xf bank_mask:0xf bound_ctrl:1
	v_mov_b32_dpp v130, v14 quad_perm:[1,0,3,2] row_mask:0xf bank_mask:0xf bound_ctrl:1
	v_mov_b32_dpp v131, v15 quad_perm:[1,0,3,2] row_mask:0xf bank_mask:0xf bound_ctrl:1
	v_mov_b32_dpp v132, v16 quad_perm:[1,0,3,2] row_mask:0xf bank_mask:0xf bound_ctrl:1
	v_mov_b32_dpp v133, v17 quad_perm:[1,0,3,2] row_mask:0xf bank_mask:0xf bound_ctrl:1
	v_mov_b32_dpp v134, v10 quad_perm:[1,0,3,2] row_mask:0xf bank_mask:0xf bound_ctrl:1
	v_mov_b32_dpp v135, v11 quad_perm:[1,0,3,2] row_mask:0xf bank_mask:0xf bound_ctrl:1
	v_mov_b32_dpp v136, v12 quad_perm:[1,0,3,2] row_mask:0xf bank_mask:0xf bound_ctrl:1
	v_mov_b32_dpp v137, v13 quad_perm:[1,0,3,2] row_mask:0xf bank_mask:0xf bound_ctrl:1
	v_mov_b32_dpp v138, v6 quad_perm:[1,0,3,2] row_mask:0xf bank_mask:0xf bound_ctrl:1
	v_mov_b32_dpp v139, v7 quad_perm:[1,0,3,2] row_mask:0xf bank_mask:0xf bound_ctrl:1
	v_mov_b32_dpp v140, v8 quad_perm:[1,0,3,2] row_mask:0xf bank_mask:0xf bound_ctrl:1
	v_mov_b32_dpp v141, v9 quad_perm:[1,0,3,2] row_mask:0xf bank_mask:0xf bound_ctrl:1
	s_waitcnt vmcnt(15)
	v_pk_mul_f32 v[50:51], v[50:51], v[114:115]
	v_pk_mul_f32 v[52:53], v[52:53], v[116:117]
	v_mov_b32_dpp v114, v2 quad_perm:[1,0,3,2] row_mask:0xf bank_mask:0xf bound_ctrl:1
	v_mov_b32_dpp v115, v3 quad_perm:[1,0,3,2] row_mask:0xf bank_mask:0xf bound_ctrl:1
	v_mov_b32_dpp v116, v4 quad_perm:[1,0,3,2] row_mask:0xf bank_mask:0xf bound_ctrl:1
	v_mov_b32_dpp v117, v5 quad_perm:[1,0,3,2] row_mask:0xf bank_mask:0xf bound_ctrl:1
	s_waitcnt vmcnt(14)
	v_pk_mul_f32 v[54:55], v[54:55], v[118:119]
	v_pk_mul_f32 v[56:57], v[56:57], v[120:121]
	s_waitcnt vmcnt(13)
	v_pk_mul_f32 v[58:59], v[58:59], v[122:123]
	v_pk_mul_f32 v[60:61], v[60:61], v[124:125]
	s_waitcnt vmcnt(12)
	v_pk_mul_f32 v[62:63], v[62:63], v[126:127]
	v_pk_mul_f32 v[64:65], v[64:65], v[128:129]
	s_waitcnt vmcnt(11)
	v_pk_mul_f32 v[66:67], v[66:67], v[130:131]
	v_pk_mul_f32 v[68:69], v[68:69], v[132:133]
	s_waitcnt vmcnt(10)
	v_pk_mul_f32 v[70:71], v[70:71], v[134:135]
	v_pk_mul_f32 v[72:73], v[72:73], v[136:137]
	s_waitcnt vmcnt(9)
	v_pk_mul_f32 v[74:75], v[74:75], v[138:139]
	v_pk_mul_f32 v[76:77], v[76:77], v[140:141]
	s_waitcnt vmcnt(8)
	v_pk_mul_f32 v[78:79], v[78:79], v[114:115]
	v_pk_mul_f32 v[80:81], v[80:81], v[116:117]
	v_cndmask_b32_e64 v53, v53, -v53, s[42:43]
	v_cndmask_b32_e64 v52, v52, -v52, s[42:43]
	v_cndmask_b32_e64 v57, v57, -v57, s[42:43]
	v_cndmask_b32_e64 v56, v56, -v56, s[42:43]
	v_cndmask_b32_e64 v60, v60, -v60, s[42:43]
	v_cndmask_b32_e64 v61, v61, -v61, s[42:43]
	v_cndmask_b32_e64 v64, v64, -v64, s[42:43]
	v_cndmask_b32_e64 v65, v65, -v65, s[42:43]
	v_cndmask_b32_e64 v68, v68, -v68, s[42:43]
	v_cndmask_b32_e64 v69, v69, -v69, s[42:43]
	v_cndmask_b32_e64 v72, v72, -v72, s[42:43]
	v_cndmask_b32_e64 v73, v73, -v73, s[42:43]
	v_cndmask_b32_e64 v76, v76, -v76, s[42:43]
	v_cndmask_b32_e64 v77, v77, -v77, s[42:43]
	v_cndmask_b32_e64 v80, v80, -v80, s[42:43]
	v_cndmask_b32_e64 v81, v81, -v81, s[42:43]
	v_cndmask_b32_e64 v51, v51, -v51, s[42:43]
	v_cndmask_b32_e64 v50, v50, -v50, s[42:43]
	v_cndmask_b32_e64 v55, v55, -v55, s[42:43]
	v_cndmask_b32_e64 v54, v54, -v54, s[42:43]
	v_cndmask_b32_e64 v58, v58, -v58, s[42:43]
	v_cndmask_b32_e64 v59, v59, -v59, s[42:43]
	v_cndmask_b32_e64 v62, v62, -v62, s[42:43]
	v_cndmask_b32_e64 v63, v63, -v63, s[42:43]
	v_cndmask_b32_e64 v66, v66, -v66, s[42:43]
	v_cndmask_b32_e64 v67, v67, -v67, s[42:43]
	v_cndmask_b32_e64 v70, v70, -v70, s[42:43]
	v_cndmask_b32_e64 v71, v71, -v71, s[42:43]
	v_cndmask_b32_e64 v74, v74, -v74, s[42:43]
	v_cndmask_b32_e64 v75, v75, -v75, s[42:43]
	v_cndmask_b32_e64 v78, v78, -v78, s[42:43]
	v_cndmask_b32_e64 v79, v79, -v79, s[42:43]
	s_waitcnt vmcnt(7)
	v_pk_fma_f32 v[4:5], v[4:5], v[84:85], v[80:81]
	s_waitcnt vmcnt(6)
	v_pk_fma_f32 v[8:9], v[8:9], v[88:89], v[76:77]
	s_waitcnt vmcnt(5)
	v_pk_fma_f32 v[12:13], v[12:13], v[92:93], v[72:73]
	s_waitcnt vmcnt(4)
	v_pk_fma_f32 v[16:17], v[16:17], v[96:97], v[68:69]
	s_waitcnt vmcnt(3)
	v_pk_fma_f32 v[20:21], v[20:21], v[100:101], v[64:65]
	s_waitcnt vmcnt(2)
	v_pk_fma_f32 v[24:25], v[24:25], v[104:105], v[60:61]
	s_waitcnt vmcnt(1)
	v_pk_fma_f32 v[28:29], v[28:29], v[108:109], v[56:57]
	s_waitcnt vmcnt(0)
	v_pk_fma_f32 v[32:33], v[32:33], v[112:113], v[52:53]
	v_pk_fma_f32 v[2:3], v[2:3], v[82:83], v[78:79]
	v_pk_fma_f32 v[6:7], v[6:7], v[86:87], v[74:75]
	v_pk_fma_f32 v[10:11], v[10:11], v[90:91], v[70:71]
	v_pk_fma_f32 v[14:15], v[14:15], v[94:95], v[66:67]
	v_pk_fma_f32 v[18:19], v[18:19], v[98:99], v[62:63]
	v_pk_fma_f32 v[22:23], v[22:23], v[102:103], v[58:59]
	v_pk_fma_f32 v[26:27], v[26:27], v[106:107], v[54:55]
	v_pk_fma_f32 v[30:31], v[30:31], v[110:111], v[50:51]
	s_nor_b64 s[52:53], s[46:47], s[52:53]
	s_and_saveexec_b64 s[16:17], s[52:53]
	s_cbranch_execnz .LBB0_763

.LBB0_766:
	s_or_b64 exec, exec, s[38:39]
	s_andn2_b64 vcc, exec, s[36:37]
	s_cbranch_vccnz .LBB0_756
	s_mul_i32 s16, s19, s4
	s_add_i32 s16, s16, s9
	s_ashr_i32 s17, s16, 31
	s_and_b32 s23, s12, 0xff
	s_lshl_b64 s[16:17], s[16:17], 8
	s_or_b32 s16, s16, s23
	v_mov_b32_e32 v2, s16
	s_mul_i32 s19, s11, s17
	v_mad_u64_u32 v[2:3], s[16:17], s11, v2, v[44:45]
	v_add_u32_e32 v3, s19, v3
	v_lshlrev_b32_e32 v8, 16, v142
	v_and_b32_e32 v9, 0xffff0000, v142
	v_lshlrev_b32_e32 v10, 16, v143
	v_and_b32_e32 v11, 0xffff0000, v143
	global_store_dwordx4 v[2:3], v[8:11], off
	s_cmpk_lt_u32 s1, 0x400
	s_cbranch_scc1 .LBB0_756
	v_lshlrev_b32_e32 v12, 16, v144
	v_and_b32_e32 v13, 0xffff0000, v144
	v_lshlrev_b32_e32 v14, 16, v145
	v_and_b32_e32 v15, 0xffff0000, v145
	global_store_dwordx4 v[2:3], v[12:15], off offset:1024
	v_lshlrev_b32_e32 v16, 16, v146
	v_and_b32_e32 v17, 0xffff0000, v146
	v_lshlrev_b32_e32 v18, 16, v147
	v_and_b32_e32 v19, 0xffff0000, v147
	global_store_dwordx4 v[2:3], v[16:19], off offset:2048
	v_lshlrev_b32_e32 v20, 16, v148
	v_and_b32_e32 v21, 0xffff0000, v148
	v_lshlrev_b32_e32 v22, 16, v149
	v_and_b32_e32 v23, 0xffff0000, v149
	global_store_dwordx4 v[2:3], v[20:23], off offset:3072
	s_branch .LBB0_756
.Lmy_vc_wait0:
	s_waitcnt vmcnt(0)
	s_branch .LBB0_766
